# weight conversion mostly moved out of the prologue: workgroups without a tile in the xq phases (ph3, ph11) and without a sixth gate/up tile (ph6) run the conversion items; prologue keeps layer-0 in/ou
# speedup vs baseline: 1.0493x; 1.0217x over previous
; #define LAS __attribute__((address_space(3)))
; __global__ void __launch_bounds__(512, 2) mega_fwd(Args a) {
;     ...
;     volatile LAS unsigned* bst = (volatile LAS unsigned*)(L + LDS_BARST); if (tid < 2) bst[tid] = 0u;
;     __syncthreads();
;     (void)xcd_barrier_post((unsigned*)(a.ws + WS_BAR), bst);
;     {
;         LAS float* tile = (LAS float*)L;
;         constexpr int I_IN = 16 * 14, I_OUT = 16 * 4, I_XQ = 16 * 2, I_XKV = 16 * 4, I_XO = 8 * 4, I_GU = 16 * 22, I_DN = 44 * 4;
;         constexpr int I_LAYER = I_IN + I_OUT + I_XQ + I_XKV + I_XO + I_GU + I_DN;
;         for (int it = bx; it < 2 * I_LAYER; it += G) {
;             const int l = it / I_LAYER; int r = it % I_LAYER;
;             unsigned char* wl = ws + WS_W + (size_t)l * W_LAYER;
;             if (r < I_IN) { conv_block_item(a.in[3] + (size_t)l * 1024 * 3474, nullptr, 3474, 1024, 1, a.in[2] + l * 1024, (bf16*)(wl + OW_IN), tile, r / 14, r % 14, tid); continue; } r -= I_IN;
_Z8mega_fwd4Args:
	s_mov_b32 s101, 0
	s_movk_i32 s100, 0x17f
	s_load_dwordx8 s[52:59], s[0:1], 0x80
	s_load_dwordx4 s[8:11], s[0:1], 0xa0
	s_load_dword s3, s[0:1], 0xb0
	s_add_u32 s4, s0, 0xb0
	s_addc_u32 s5, s1, 0
	v_readfirstlane_b32 s33, v0
	v_writelane_b32 v253, s4, 0
	v_cmp_gt_u32_e32 vcc, 2, v0
	s_nop 0
	v_writelane_b32 v253, s5, 1
	s_and_saveexec_b64 s[6:7], vcc
	v_lshl_add_u32 v1, v0, 2, 0
	v_add_u32_e32 v1, 0x23fc0, v1
	v_mov_b32_e32 v2, 0
	ds_write_b32 v1, v2
	s_waitcnt lgkmcnt(0)
	v_writelane_b32 v253, s3, 2
	s_or_b64 exec, exec, s[6:7]
	s_add_u32 s28, s10, 0xc0000
	v_writelane_b32 v253, s8, 3
	s_barrier
	s_nop 0
	v_writelane_b32 v253, s9, 4
	v_writelane_b32 v253, s10, 5
	v_writelane_b32 v253, s11, 6
	s_addc_u32 s29, s11, 0
	s_getreg_b32 s6, hwreg(HW_REG_XCC_ID, 0, 4)
	v_cmp_eq_u32_e64 s[4:5], 0, v0
	s_mov_b64 s[10:11], exec
	s_nop 0
	v_writelane_b32 v253, s4, 7
	s_nop 1
	v_writelane_b32 v253, s5, 8
	s_and_b64 s[4:5], s[10:11], s[4:5]
	s_mov_b64 exec, s[4:5]
	s_cbranch_execz .LBB0_5
	s_mov_b64 s[4:5], exec
	v_mbcnt_lo_u32_b32 v1, s4, 0
	v_mbcnt_hi_u32_b32 v1, s5, v1
	v_cmp_eq_u32_e32 vcc, 0, v1
	s_and_b64 s[8:9], exec, vcc
	s_mov_b64 exec, s[8:9]
	s_cbranch_execz .LBB0_5
	s_lshl_b32 s6, s6, 8
	s_and_b32 s6, s6, 0xf00
	s_bcnt1_i32_b64 s4, s[4:5]
	v_mov_b32_e32 v1, s6
	v_mov_b32_e32 v2, s4
	global_atomic_add v1, v2, s[28:29] offset:1024
.LBB0_5:
	s_or_b64 exec, exec, s[10:11]
	s_load_dwordx16 s[12:27], s[0:1], 0x0
	s_load_dwordx16 s[36:51], s[0:1], 0x40
	v_writelane_b32 v253, s2, 9
	s_cmp_gt_i32 s2, s100
	s_cbranch_scc1 .Lconv_exit
.Lconv_bb6:
	v_readlane_b32 s0, v253, 3
	v_lshrrev_b32_e32 v12, 6, v0
	s_movk_i32 s0, 0x404
	v_mov_b32_e32 v2, 0x2020
	v_mad_u32_u24 v30, v12, s0, v2
	v_mov_b32_e32 v2, 0x4040
	v_readlane_b32 s2, v253, 5
	v_mad_u32_u24 v32, v12, s0, v2
	v_mov_b32_e32 v2, 0x6060
	v_readlane_b32 s3, v253, 6
	s_add_u32 s72, s2, 0x100000
	v_mad_u32_u24 v34, v12, s0, v2
	v_lshlrev_b32_e32 v2, 3, v0
	s_addc_u32 s73, s3, 0
	v_lshlrev_b32_e32 v3, 2, v0
	v_lshrrev_b32_e32 v39, 3, v0
	v_and_b32_e32 v2, 56, v2
	v_and_b32_e32 v10, 0xfc, v3
	v_mul_u32_u24_e32 v4, 0x404, v2
	v_lshlrev_b32_e32 v6, 2, v39
	s_movk_i32 s0, 0x80
	s_waitcnt lgkmcnt(0)
	s_cmp_lg_u64 s[50:51], 0
	v_add3_u32 v40, 0, v4, v6
	s_cselect_b64 s[30:31], -1, 0
	v_mov_b32_e32 v4, s55
	v_mov_b32_e32 v6, s53
	v_cmp_gt_u32_e32 vcc, s0, v10
	s_cmp_lg_u64 s[42:43], 0
	v_lshl_add_u32 v1, v10, 2, 0
	v_mul_u32_u24_e32 v5, 0x404, v12
	v_cndmask_b32_e32 v17, v4, v6, vcc
	v_mov_b32_e32 v4, s54
	v_mov_b32_e32 v6, s52
	s_cselect_b64 s[34:35], -1, 0
	s_cmp_lg_u64 s[40:41], 0
	v_readlane_b32 s1, v253, 4
	v_mov_b32_e32 v15, 0
	v_cndmask_b32_e32 v16, v4, v6, vcc
	v_and_b32_e32 v4, 0x7c, v3
	s_cselect_b64 s[52:53], -1, 0
	s_cmp_lg_u64 s[16:17], 0
	v_readlane_b32 s87, v253, 9
	v_readlane_b32 s0, v253, 2
	v_add_u32_e32 v44, v1, v5
	s_mov_b32 s1, 0
	v_or_b32_e32 v11, 8, v12
	v_or_b32_e32 v31, 16, v12
	v_or_b32_e32 v33, 24, v12
	v_or_b32_e32 v35, 32, v12
	v_or_b32_e32 v36, 40, v12
	v_or_b32_e32 v37, 48, v12
	v_or_b32_e32 v38, 56, v12
	v_or_b32_e32 v41, 64, v39
	v_or_b32_e32 v42, 0x80, v39
	v_or_b32_e32 v43, 0xc0, v39
	s_cselect_b64 s[54:55], -1, 0
	v_mov_b32_e32 v13, v15
	s_lshl_b32 s74, s87, 8
	s_lshl_b32 s75, s0, 8
	s_lshl_b32 s76, s87, 4
	s_lshl_b32 s77, s0, 4
	s_lshl_b32 s78, s87, 5
	s_lshl_b32 s79, s0, 5
	v_add_u32_e32 v45, 0x2020, v44
	v_add_u32_e32 v46, 0x2028, v44
	v_add_u32_e32 v47, 0x4040, v44
	v_add_u32_e32 v48, 0x4048, v44
	v_add_u32_e32 v49, 0x6060, v44
	v_add_u32_e32 v50, 0x6068, v44
	v_add_u32_e32 v51, 0x8080, v44
	v_add_u32_e32 v52, 0x8088, v44
	v_add_u32_e32 v53, 0xa0a0, v44
	v_add_u32_e32 v54, 0xa0a8, v44
	v_add_u32_e32 v55, 0xc0c0, v44
	v_add_u32_e32 v56, 0xc0c8, v44
	v_add_u32_e32 v57, 0xe0e0, v44
	v_add_u32_e32 v58, 0xe0e8, v44
	s_movk_i32 s80, 0x7fff
	s_mov_b32 s81, 0xffff0000
	v_lshlrev_b32_e32 v18, 2, v4
	s_movk_i32 s82, 0x2c00
	s_movk_i32 s83, 0x47f
	s_movk_i32 s84, 0xd7f
	s_movk_i32 s85, 0xd85
	s_movk_i32 s86, 0xd92
	v_lshlrev_b32_e32 v14, 2, v10
	v_lshlrev_b32_e32 v20, 1, v2
	v_add_u32_e32 v59, 4, v40
	v_add_u32_e32 v60, 8, v40
	v_add_u32_e32 v61, 12, v40
	v_add_u32_e32 v62, 16, v40
	v_add_u32_e32 v63, 20, v40
	v_add_u32_e32 v64, 24, v40
	v_add_u32_e32 v65, 28, v40
	v_mov_b32_e32 v66, 0xb00000
	s_branch .LBB0_9

; __global__ void __launch_bounds__(512, 2) mega_fwd(Args a) {
;     ...
;         for (int it = bx; it < 2 * I_LAYER; it += G) {
.LBB0_8:
	v_readlane_b32 s0, v253, 2
	s_add_i32 s87, s87, s0
	s_add_i32 s74, s74, s75
	s_add_i32 s76, s76, s77
	s_add_i32 s78, s78, s79
	s_cmp_gt_i32 s87, s100
	s_cbranch_scc1 .Lconv_exit

; __global__ void __launch_bounds__(512, 2) mega_fwd(Args a) {
;     ...
;         for (int it = bx; it < 2 * I_LAYER; it += G) {
;             const int l = it / I_LAYER; int r = it % I_LAYER;
;             unsigned char* wl = ws + WS_W + (size_t)l * W_LAYER;
;             if (r < I_IN) { conv_block_item(a.in[3] + (size_t)l * 1024 * 3474, nullptr, 3474, 1024, 1, a.in[2] + l * 1024, (bf16*)(wl + OW_IN), tile, r / 14, r % 14, tid); continue; } r -= I_IN;
;             if (r < I_OUT) { conv_block_item(a.in[9] + (size_t)l * 1024 * 1024, nullptr, 1024, 1024, 0, nullptr, (bf16*)(wl + OW_OUT), tile, r / 4, r % 4, tid); continue; } r -= I_OUT;
;             if (r < I_XQ) { conv_block_item(a.in[12] + (size_t)l * 1024 * 512, nullptr, 512, 1024, 0, a.in[10] + l * 1024, (bf16*)(wl + OW_XQ), tile, r / 2, r % 2, tid); continue; } r -= I_XQ;
;             if (r < I_XKV) { conv_block_item(a.in[13] + (size_t)l * 1024 * 1024, nullptr, 1024, 1024, 0, a.in[11] + l * 1024, (bf16*)(wl + OW_XKV), tile, r / 4, r % 4, tid); continue; } r -= I_XKV;
;             if (r < I_XO) { conv_block_item(a.in[14] + (size_t)l * 512 * 1024, nullptr, 1024, 512, 0, nullptr, (bf16*)(wl + OW_XO), tile, r / 4, r % 4, tid); continue; } r -= I_XO;
;             if (r < I_GU) { conv_block_item(a.in[16] + (size_t)l * 1024 * DFF, a.in[17] + (size_t)l * 1024 * DFF, DFF, 1024, 2, a.in[15] + l * 1024, (bf16*)(wl + OW_GU), tile, r / 22, r % 22, tid); continue; } r -= I_GU;
;             conv_block_item(a.in[18] + (size_t)l * DFF * 1024, nullptr, 1024, DFF, 0, nullptr, (bf16*)(wl + OW_DN), tile, r / 4, r % 4, tid);
;         }
;     ...
;         if (k == 0 || k == 3) {
;             const int j0 = (ph == 0) ? 0 : 2;
;             for (int j = j0; j < 3; ++j) {
;                 pg8::Gemm g; pg8::EpiScaleBf16 E; int off = 0;
;                 if (j < 2) { g = pg8::Gemm{memb, (const bf16*)(ws + WS_W + (size_t)j * W_LAYER + OW_XKV), MROWS, 1024, 1024}; E = pg8::EpiScaleBf16{kvb + (size_t)j * MROWS * 1024, 1024, ssqm}; off = 128 + 32 * j; }
;                 else if (k == 0) { g = pg8::Gemm{hb, (const bf16*)(wl + OW_IN), M, NU, 1024}; E = pg8::EpiScaleBf16{ub, NU, ssq + (size_t)(3 * l) * M * 16}; }
;                 else { g = pg8::Gemm{hb, (const bf16*)(wl + OW_XQ), M, DX, 1024}; E = pg8::EpiScaleBf16{qxb, DX, ssq + (size_t)(3 * l + 1) * M * 16}; }
;                 pg8::OffsetOrder Sc; Sc.init(g.M, g.N, G, bx, off);
.Lconv_exit:
	s_cmp_eq_u32 s101, 0
	s_cbranch_scc1 .Lconv_after1
	s_cmp_eq_u32 s101, 1
	s_cbranch_scc1 .Lconv_after2
	s_branch .Lfiller_ret
.Lconv_after1:
	s_mov_b32 s101, 1
	s_movk_i32 s100, 0x52f
	v_readlane_b32 s2, v253, 9
	s_nop 3
	s_addk_i32 s2, 0x4f0
	s_nop 0
	v_writelane_b32 v253, s2, 9
	s_branch .Lconv_reenter
.Lconv_after2:
	v_readlane_b32 s2, v253, 9
	s_nop 3
	s_addk_i32 s2, 0xfb10
	s_nop 0
	v_writelane_b32 v253, s2, 9
	s_branch .LBB0_488
.Lconv_reenter:
	v_readlane_b32 s0, v253, 0
	v_readlane_b32 s1, v253, 1
	v_readfirstlane_b32 s33, v0
	s_nop 3
	s_sub_u32 s0, s0, 0xb0
	s_subb_u32 s1, s1, 0
	s_load_dwordx8 s[52:59], s[0:1], 0x80
	s_load_dwordx4 s[8:11], s[0:1], 0xa0
	s_load_dwordx16 s[12:27], s[0:1], 0x0
	s_load_dwordx16 s[36:51], s[0:1], 0x40
	v_readlane_b32 s2, v253, 9
	s_waitcnt lgkmcnt(0)
	s_add_u32 s28, s10, 0xc0000
	s_addc_u32 s29, s11, 0
	s_cmp_gt_i32 s2, s100
	s_cbranch_scc1 .Lconv_exit
	s_branch .Lconv_bb6
.Lfiller_chk:
	s_cmp_eq_u32 s10, 2
	s_cbranch_scc0 .LBB0_668
	s_cmp_eq_u32 s78, 3
	s_cbranch_scc1 .Lfiller_a
	s_cmp_eq_u32 s78, 11
	s_cbranch_scc1 .Lfiller_b
	s_branch .LBB0_668
.Lfiller_a:
	s_movk_i32 s100, 0x3af
	s_movk_i32 s2, 0x180
	s_branch .Lfiller_go
.Lfiller_b:
	s_movk_i32 s100, 0x75f
	s_movk_i32 s2, 0x530
.Lfiller_go:
	s_mov_b32 s101, s78
	s_sub_i32 s3, s51, s84
	s_add_i32 s2, s2, s3
	v_readlane_b32 s4, v253, 2
	v_readlane_b32 s5, v253, 9
	s_nop 3
	v_writelane_b32 v255, s4, 40
	v_writelane_b32 v255, s5, 41
	s_sub_i32 s4, s4, s84
	s_nop 0
	v_writelane_b32 v253, s4, 2
	v_writelane_b32 v253, s2, 9
	s_branch .Lconv_reenter
.Lfiller_ret:
	v_readlane_b32 s4, v255, 40
	v_readlane_b32 s5, v255, 41
	s_nop 3
	v_writelane_b32 v253, s4, 2
	v_writelane_b32 v253, s5, 9
	s_mov_b32 s74, s5
	s_mov_b32 s75, s4
	s_lshl_b32 s76, s75, 3
	v_readlane_b32 s60, v253, 3
	v_readlane_b32 s61, v253, 4
	v_readlane_b32 s62, v253, 5
	v_readlane_b32 s63, v253, 6
	v_mbcnt_lo_u32_b32 v1, -1, 0
	s_nop 3
	s_cmpk_lt_i32 s74, 0x100
	s_cselect_b64 s[0:1], -1, 0
	v_writelane_b32 v253, s0, 11
	s_ashr_i32 s77, s74, 31
	s_ashr_i32 s3, s75, 31
	v_writelane_b32 v253, s1, 12
	s_lshr_b32 s0, s77, 29
	s_add_i32 s0, s74, s0
	s_ashr_i32 s1, s0, 3
	s_and_b32 s0, s0, -8
	s_sub_i32 s2, s74, s0
	s_lshl_b32 s0, s2, 5
	s_cmpk_lt_i32 s74, 0x580
	v_writelane_b32 v253, s3, 13
	s_cselect_b64 s[4:5], -1, 0
	v_writelane_b32 v253, s4, 14
	s_mov_b32 s78, s101
	s_mov_b32 s79, 0
	s_movk_i32 s83, 0x2000
	v_writelane_b32 v253, s5, 15
	s_add_u32 s4, s60, 0xe00000
	s_addc_u32 s5, s61, 0
	v_writelane_b32 v253, s4, 16
	s_add_u32 s3, s60, 0xf00000
	v_mov_b32_e32 v3, 0
	v_writelane_b32 v253, s5, 17
	v_writelane_b32 v253, s3, 18
	s_addc_u32 s3, s61, 0
	v_writelane_b32 v253, s3, 19
	s_and_b32 s3, s74, 7
	v_writelane_b32 v253, s3, 20
	s_add_i32 s3, s75, s74
	v_writelane_b32 v253, s3, 21
	s_cmp_lt_i32 s2, 0
	s_mul_i32 s3, s2, 33
	s_cselect_b32 s0, s3, s0
	s_movk_i32 s3, 0xb1
	s_cselect_b32 s3, s3, 0xb0
	s_add_i32 s0, s0, s1
	s_ashr_i32 s4, s0, 31
	s_lshr_b32 s4, s4, 28
	s_add_i32 s4, s0, s4
	s_ashr_i32 s5, s4, 4
	s_and_b32 s4, s4, 0xfff0
	s_mul_i32 s2, s2, s3
	s_sub_i32 s4, s0, s4
	s_add_i32 s2, s2, s1
	s_bfe_i32 s0, s4, 0x80000
	s_mul_hi_i32 s1, s2, 0x2e8ba2e9
	s_bfe_u32 s0, s0, 0x2000d
	s_lshr_b32 s3, s1, 31
	s_ashr_i32 s1, s1, 4
	s_add_i32 s6, s4, s0
	s_add_i32 s1, s1, s3
	s_bfe_i32 s0, s6, 0x80000
	s_and_b32 s6, s6, 0xfc
	s_lshl_b32 s3, s1, 2
	s_mulk_i32 s1, 0x58
	s_sub_i32 s4, s4, s6
	s_sub_i32 s1, s2, s1
	s_lshl_b32 s5, s5, 2
	s_sext_i32_i16 s7, s0
	s_sext_i32_i8 s4, s4
	s_bfe_i32 s2, s1, 0x80000
	s_add_i32 s6, s5, s4
	s_ashr_i32 s4, s7, 2
	s_bfe_u32 s2, s2, 0x2000d
	v_writelane_b32 v253, s4, 22
	s_add_i32 s4, s1, s2
	s_bfe_i32 s2, s4, 0x80000
	s_and_b32 s4, s4, 0xfc
	s_sub_i32 s1, s1, s4
	s_abs_i32 s4, s75
	s_waitcnt lgkmcnt(0)
	v_cvt_f32_u32_e32 v2, s4
	s_sext_i32_i16 s5, s2
	s_sext_i32_i8 s1, s1
	s_add_i32 s10, s3, s1
	s_ashr_i32 s1, s5, 2
	v_writelane_b32 v253, s1, 23
	s_mov_b32 s8, s10
	s_ashr_i32 s11, s10, 31
	v_rcp_iflag_f32_e32 v2, v2
	v_writelane_b32 v253, s8, 24
	s_lshr_b32 s2, s5, 2
	s_bfe_i64 s[2:3], s[2:3], 0x100000
	v_writelane_b32 v253, s9, 25
	s_lshl_b64 s[8:9], s[10:11], 19
	v_writelane_b32 v253, s8, 26
	s_lshl_b64 s[2:3], s[2:3], 19
	v_mul_f32_e32 v2, 0x4f7ffffe, v2
	v_writelane_b32 v253, s9, 27
	v_writelane_b32 v253, s2, 28
	v_cvt_u32_f32_e32 v2, v2
	s_lshr_b32 s0, s7, 2
	v_writelane_b32 v253, s3, 29
	v_writelane_b32 v253, s6, 30
	s_ashr_i32 s1, s6, 31
	v_writelane_b32 v253, s1, 31
	s_bfe_i64 s[0:1], s[0:1], 0x100000
	v_writelane_b32 v253, s0, 32
	s_movk_i32 s88, 0x4000
	s_mov_b64 s[92:93], 0x80
	v_writelane_b32 v253, s1, 33
	s_sub_i32 s0, 0, s4
	v_readfirstlane_b32 s1, v2
	s_mul_i32 s0, s0, s1
	s_mul_hi_u32 s0, s1, s0
	v_writelane_b32 v253, s4, 34
	s_add_i32 s0, s1, s0
	v_writelane_b32 v253, s0, 35
	s_lshl_b32 s0, s74, 10
	v_writelane_b32 v253, s0, 36
	s_lshl_b32 s0, s75, 10
	v_writelane_b32 v253, s0, 37
	s_add_u32 s0, s62, 0xf010080
	v_writelane_b32 v253, s0, 38
	s_addc_u32 s0, s63, 0
	v_writelane_b32 v253, s0, 39
	s_add_i32 s0, 0, 0x23fc0
	v_writelane_b32 v253, s0, 40
	s_add_i32 s0, 0, 0x23fc4
	v_writelane_b32 v253, s0, 41
	v_writelane_b32 v253, s76, 42
	v_mov_b32_e32 v208, 0x358637bd
	s_mov_b32 s99, 0x800000
	v_writelane_b32 v253, s77, 43
	s_mov_b32 s70, 0xbfb8aa3b
	s_movk_i32 s82, 0xe00
	s_movk_i32 s71, 0x1c00
	s_movk_i32 s73, 0x5a
	s_movk_i32 s95, 0x1bf
	s_movk_i32 s72, 0x1000
	v_mov_b32_e32 v209, 0x4000
	s_mov_b32 s94, 0xf000
	s_mov_b32 s96, 0x3f317217
	v_mov_b32_e32 v210, 1
	v_mov_b64_e32 v[198:199], 0x100
	v_mov_b64_e32 v[200:201], 0xff
	v_mbcnt_hi_u32_b32 v214, -1, v1
	v_mov_b32_e32 v215, 0x1c00
	v_mov_b32_e32 v216, 0xf149f2ca
	v_mov_b32_e32 v217, 0x7c
	v_mov_b32_e32 v218, 0x41b17218
	s_mov_b32 s85, 0
	v_writelane_b32 v253, s77, 44
	s_mov_b32 s80, s62
	s_mov_b32 s81, s63
	s_mov_b32 s101, 0
	s_branch .LBB0_818

;     __device__ void init(int M, int N, int G, int c, int off) { b.init(M, N, G, (c + G - (off % G)) % G); }
; #define PG8_WAIT_V(n) asm volatile("s_waitcnt vmcnt(" #n ")" ::: "memory")
; #define PG8_BAR __builtin_amdgcn_s_barrier()
; #define GEMM_PHASE(EpiT, SchedT, g, Sc, E) pg8::gemm_phase<EpiT, SchedT, true, true>(L, g, Sc, E)
; template <class Epi, class Sched, bool ALIGN_EPI = false, bool SP2 = false>
; __device__ __forceinline__ void gemm_phase(PG8_LAS unsigned char* lds, const Gemm g, const Sched& S, const Epi& E) {
;     ...
;     PG8_WAIT_V(0);
;     if constexpr (!ALIGN_EPI) { if (wr == 0) PG8_BAR; }
;     PG8_BAR;
; __global__ void __launch_bounds__(512, 2) mega_fwd(Args a) {
;     ...
;         } else if (k == 6) {
;             pg8::Gemm g{hb, (const bf16*)(wl + OW_GU), M, 2 * DFF, 1024}; pg8::StaticOrder Sc; Sc.init(M, 2 * DFF, G, bx);
;             pg8::EpiSwiglu E{actb, DFF, ssq + (size_t)(3 * l + 2) * M * 16};
;             GEMM_PHASE(pg8::EpiSwiglu, pg8::StaticOrder, g, Sc, E);
.LBB0_617:
	s_waitcnt vmcnt(0)
	s_barrier
	s_cmp_eq_u32 s78, 6
	s_cbranch_scc0 .LBB0_618
	v_readlane_b32 s2, v253, 9
	v_readlane_b32 s3, v253, 2
	s_nop 3
	s_mul_i32 s3, s3, 5
	s_sub_i32 s3, 0x580, s3
	s_cmp_ge_i32 s2, s3
	s_cbranch_scc0 .LBB0_618
	s_mov_b32 s51, s2
	s_mov_b32 s84, s3
	s_movk_i32 s100, 0x4ef
	s_movk_i32 s2, 0x3b0
	s_branch .Lfiller_go

; __global__ void __launch_bounds__(512, 2) mega_fwd(Args a) {
	.amdhsa_kernel _Z8mega_fwd4Args
		.amdhsa_group_segment_fixed_size 0
		.amdhsa_private_segment_fixed_size 0
		.amdhsa_kernarg_size 432
		.amdhsa_user_sgpr_count 2
		.amdhsa_user_sgpr_dispatch_ptr 0
		.amdhsa_user_sgpr_queue_ptr 0
		.amdhsa_user_sgpr_kernarg_segment_ptr 1
		.amdhsa_user_sgpr_dispatch_id 0
		.amdhsa_user_sgpr_kernarg_preload_length 0
		.amdhsa_user_sgpr_kernarg_preload_offset 0
		.amdhsa_user_sgpr_private_segment_size 0
		.amdhsa_uses_dynamic_stack 0
		.amdhsa_enable_private_segment 0
		.amdhsa_system_sgpr_workgroup_id_x 1
		.amdhsa_system_sgpr_workgroup_id_y 0
		.amdhsa_system_sgpr_workgroup_id_z 0
		.amdhsa_system_sgpr_workgroup_info 0
		.amdhsa_system_vgpr_workitem_id 0
		.amdhsa_next_free_vgpr 256
		.amdhsa_next_free_sgpr 102
		.amdhsa_accum_offset 256
		.amdhsa_reserve_vcc 1
		.amdhsa_float_round_mode_32 0
		.amdhsa_float_round_mode_16_64 0
		.amdhsa_float_denorm_mode_32 3
		.amdhsa_float_denorm_mode_16_64 3
		.amdhsa_dx10_clamp 1
		.amdhsa_ieee_mode 1
		.amdhsa_fp16_overflow 0
		.amdhsa_tg_split 0
		.amdhsa_exception_fp_ieee_invalid_op 0
		.amdhsa_exception_fp_denorm_src 0
		.amdhsa_exception_fp_ieee_div_zero 0
		.amdhsa_exception_fp_ieee_overflow 0
		.amdhsa_exception_fp_ieee_underflow 0
		.amdhsa_exception_fp_ieee_inexact 0
		.amdhsa_exception_int_div_zero 0
	.end_amdhsa_kernel

; __global__ void __launch_bounds__(512, 2) mega_fwd(Args a) {
amdhsa.kernels:
  - .agpr_count:     0
    .args:
      - .offset:         0
        .size:           176
        .value_kind:     by_value
      - .offset:         176
        .size:           4
        .value_kind:     hidden_block_count_x
      - .offset:         180
        .size:           4
        .value_kind:     hidden_block_count_y
      - .offset:         184
        .size:           4
        .value_kind:     hidden_block_count_z
      - .offset:         188
        .size:           2
        .value_kind:     hidden_group_size_x
      - .offset:         190
        .size:           2
        .value_kind:     hidden_group_size_y
      - .offset:         192
        .size:           2
        .value_kind:     hidden_group_size_z
      - .offset:         194
        .size:           2
        .value_kind:     hidden_remainder_x
      - .offset:         196
        .size:           2
        .value_kind:     hidden_remainder_y
      - .offset:         198
        .size:           2
        .value_kind:     hidden_remainder_z
      - .offset:         216
        .size:           8
        .value_kind:     hidden_global_offset_x
      - .offset:         224
        .size:           8
        .value_kind:     hidden_global_offset_y
      - .offset:         232
        .size:           8
        .value_kind:     hidden_global_offset_z
      - .offset:         240
        .size:           2
        .value_kind:     hidden_grid_dims
      - .offset:         296
        .size:           4
        .value_kind:     hidden_dynamic_lds_size
    .group_segment_fixed_size: 0
    .kernarg_segment_align: 8
    .kernarg_segment_size: 432
    .language:       OpenCL C
    .language_version:
      - 2
      - 0
    .max_flat_workgroup_size: 512
    .name:           _Z8mega_fwd4Args
    .private_segment_fixed_size: 0
    .sgpr_count:     108
    .sgpr_spill_count: 149
    .symbol:         _Z8mega_fwd4Args.kd
    .uniform_work_group_size: 1
    .uses_dynamic_stack: false
    .vgpr_count:     256
    .vgpr_spill_count: 0
    .wavefront_size: 64
